# speedup vs baseline: 1.0004x; 1.0004x over previous
; __device__ __forceinline__ void phase_scan(const Params& p, int wid_s, char* shm) {
;     ...
;       if (ch < mynch) {
;         const float* cb = buf + (ch & 1) * BUF_F + cg8 * 8;
;         const float* cv = buf + (ch & 1) * BUF_F + 320 + rg * 2;
;         const float* ck = buf + (ch & 1) * BUF_F + 384;
;         float* yw = ybuf + (ch & 1) * (SCAN_CH * 64) + rg * 2;
; #pragma unroll 8
;         for (int s = 0; s < SCAN_CH; ++s) {
;           const float* rec = cb + s * SCAN_STEP_F;
;           v2f kk[4], wr8[4], w8[4], ka8[4], kd8[4];
; #pragma unroll
;           for (int c = 0; c < 4; ++c) {
;             kk[c] = *(const v2f*)(rec + 0 + c * 2);
;             wr8[c] = *(const v2f*)(rec + 64 + c * 2);
;             w8[c] = *(const v2f*)(rec + 128 + c * 2);
;             ka8[c] = *(const v2f*)(rec + 192 + c * 2);
;             kd8[c] = *(const v2f*)(rec + 256 + c * 2);
;           }
;           v2f vv = *(const v2f*)(cv + s * SCAN_STEP_F);
;           v2f krdr = *(const v2f*)(ck + s * SCAN_STEP_F);
;           v2f p0 = S0[0] * kk[0], p1 = S1[0] * kk[0], q0 = S0[0] * wr8[0], q1 = S1[0] * wr8[0];
; #pragma unroll
;           for (int c = 1; c < 4; ++c) {
;             p0 += S0[c] * kk[c]; p1 += S1[c] * kk[c];
;             q0 += S0[c] * wr8[c]; q1 += S1[c] * wr8[c];
;           }
;           float p0s = red8(p0.x + p0.y), p1s = red8(p1.x + p1.y);
;           float q0s = red8(q0.x + q0.y), q1s = red8(q1.x + q1.y);
;           float sa0 = -p0s, sa1 = -p1s;
;           v2f yy;
;           yy.x = q0s + sa0 * krdr.x + vv.x * krdr.y;
;           yy.y = q1s + sa1 * krdr.x + vv.y * krdr.y;
;           *(v2f*)(yw + s * 64) = yy;
;           v2f sa0v = v2f{sa0, sa0}, sa1v = v2f{sa1, sa1}, v0v = v2f{vv.x, vv.x}, v1v = v2f{vv.y, vv.y};
; #pragma unroll
;           for (int c = 0; c < 4; ++c) {
;             S0[c] = S0[c] * w8[c] + sa0v * ka8[c] + v0v * kd8[c];
;             S1[c] = S1[c] * w8[c] + sa1v * ka8[c] + v1v * kd8[c];
;           }
.LBB0_864:
	s_or_b64 exec, exec, s[40:41]
	v_cmp_lt_u32_e32 vcc, s64, v121
	s_and_saveexec_b64 s[40:41], vcc
	s_cbranch_execz .LBB0_867
	v_cndmask_b32_e64 v2, 0, 1, s[26:27]
	v_mul_lo_u32 v3, v2, s45
	v_add_u32_e32 v0, v114, v3
	v_add_u32_e32 v62, v115, v3
	v_add_u32_e32 v64, v116, v3
	v_lshl_add_u32 v79, v2, 12, v117
	s_mov_b32 s42, 16
	s_mov_b32 s98, 0x01010101
	s_mov_b32 s99, 0x01010101
	s_mov_b64 s[100:101], exec
	ds_read_b128 v[160:163], v0 offset:0
	ds_read_b128 v[164:167], v0 offset:16
	ds_read_b128 v[168:171], v0 offset:256
	ds_read_b128 v[172:175], v0 offset:272
	ds_read_b128 v[176:179], v0 offset:512
	ds_read_b128 v[180:183], v0 offset:528
	ds_read_b128 v[184:187], v0 offset:768
	ds_read_b128 v[188:191], v0 offset:784
	ds_read_b128 v[192:195], v0 offset:1024
	ds_read_b128 v[196:199], v0 offset:1040
	ds_read_b64 v[200:201], v62 offset:0
	ds_read_b64 v[202:203], v64 offset:0
.LBB0_866:
	ds_read_b128 v[204:207], v0 offset:1552
	ds_read_b128 v[208:211], v0 offset:1568
	ds_read_b128 v[212:215], v0 offset:1808
	ds_read_b128 v[216:219], v0 offset:1824
	ds_read_b128 v[220:223], v0 offset:2064
	ds_read_b128 v[224:227], v0 offset:2080
	ds_read_b128 v[228:231], v0 offset:2320
	ds_read_b128 v[232:235], v0 offset:2336
	ds_read_b128 v[236:239], v0 offset:2576
	ds_read_b128 v[240:243], v0 offset:2592
	ds_read_b64 v[244:245], v62 offset:1552
	ds_read_b64 v[246:247], v64 offset:1552
	v_add_u32_e32 v122, 0x19600, v79
	s_waitcnt lgkmcnt(12)
	v_pk_mul_f32 v[24:25], v[10:11], v[162:163]
	v_pk_mul_f32 v[26:27], v[18:19], v[162:163]
	v_pk_mul_f32 v[28:29], v[10:11], v[170:171]
	v_pk_mul_f32 v[30:31], v[18:19], v[170:171]
	v_pk_fma_f32 v[24:25], v[8:9], v[160:161], v[24:25]
	v_pk_fma_f32 v[26:27], v[16:17], v[160:161], v[26:27]
	v_pk_fma_f32 v[28:29], v[8:9], v[168:169], v[28:29]
	v_pk_fma_f32 v[30:31], v[16:17], v[168:169], v[30:31]
	v_pk_fma_f32 v[24:25], v[12:13], v[164:165], v[24:25]
	v_pk_fma_f32 v[26:27], v[20:21], v[164:165], v[26:27]
	v_pk_fma_f32 v[28:29], v[12:13], v[172:173], v[28:29]
	v_pk_fma_f32 v[30:31], v[20:21], v[172:173], v[30:31]
	v_pk_fma_f32 v[24:25], v[14:15], v[166:167], v[24:25]
	v_pk_fma_f32 v[26:27], v[22:23], v[166:167], v[26:27]
	v_pk_fma_f32 v[28:29], v[14:15], v[174:175], v[28:29]
	v_pk_fma_f32 v[30:31], v[22:23], v[174:175], v[30:31]
	v_add_f32_e32 v32, v24, v25
	v_add_f32_e32 v33, v26, v27
	v_add_f32_e32 v34, v28, v29
	v_add_f32_e32 v35, v30, v31
	v_add_f32_dpp v32, v32, v32 quad_perm:[1,0,3,2] row_mask:0xf bank_mask:0xf bound_ctrl:1
	v_add_f32_dpp v33, v33, v33 quad_perm:[1,0,3,2] row_mask:0xf bank_mask:0xf bound_ctrl:1
	v_add_f32_dpp v34, v34, v34 quad_perm:[1,0,3,2] row_mask:0xf bank_mask:0xf bound_ctrl:1
	v_add_f32_dpp v35, v35, v35 quad_perm:[1,0,3,2] row_mask:0xf bank_mask:0xf bound_ctrl:1
	v_add_f32_dpp v32, v32, v32 quad_perm:[2,3,0,1] row_mask:0xf bank_mask:0xf bound_ctrl:1
	v_add_f32_dpp v33, v33, v33 quad_perm:[2,3,0,1] row_mask:0xf bank_mask:0xf bound_ctrl:1
	v_add_f32_dpp v34, v34, v34 quad_perm:[2,3,0,1] row_mask:0xf bank_mask:0xf bound_ctrl:1
	v_add_f32_dpp v35, v35, v35 quad_perm:[2,3,0,1] row_mask:0xf bank_mask:0xf bound_ctrl:1
	v_add_f32_dpp v32, v32, v32 row_half_mirror row_mask:0xf bank_mask:0xf bound_ctrl:1
	v_add_f32_dpp v33, v33, v33 row_half_mirror row_mask:0xf bank_mask:0xf bound_ctrl:1
	v_add_f32_dpp v34, v34, v34 row_half_mirror row_mask:0xf bank_mask:0xf bound_ctrl:1
	v_add_f32_dpp v35, v35, v35 row_half_mirror row_mask:0xf bank_mask:0xf bound_ctrl:1
	v_pk_mul_f32 v[36:37], v[184:185], v[32:33] op_sel_hi:[1,0] neg_lo:[0,1] neg_hi:[0,1]
	v_pk_mul_f32 v[44:45], v[184:185], v[32:33] op_sel:[0,1] neg_lo:[0,1] neg_hi:[0,1]
	v_pk_mul_f32 v[38:39], v[186:187], v[32:33] op_sel_hi:[1,0] neg_lo:[0,1] neg_hi:[0,1]
	v_pk_mul_f32 v[46:47], v[186:187], v[32:33] op_sel:[0,1] neg_lo:[0,1] neg_hi:[0,1]
	v_pk_mul_f32 v[40:41], v[188:189], v[32:33] op_sel_hi:[1,0] neg_lo:[0,1] neg_hi:[0,1]
	v_pk_mul_f32 v[48:49], v[188:189], v[32:33] op_sel:[0,1] neg_lo:[0,1] neg_hi:[0,1]
	v_pk_mul_f32 v[42:43], v[190:191], v[32:33] op_sel_hi:[1,0] neg_lo:[0,1] neg_hi:[0,1]
	v_pk_mul_f32 v[50:51], v[190:191], v[32:33] op_sel:[0,1] neg_lo:[0,1] neg_hi:[0,1]
	v_pk_fma_f32 v[34:35], v[202:203], v[32:33], v[34:35] op_sel_hi:[0,1,1] neg_lo:[1,0,0] neg_hi:[1,0,0]
	v_pk_fma_f32 v[36:37], v[8:9], v[176:177], v[36:37]
	v_pk_fma_f32 v[44:45], v[16:17], v[176:177], v[44:45]
	v_pk_fma_f32 v[38:39], v[10:11], v[178:179], v[38:39]
	v_pk_fma_f32 v[46:47], v[18:19], v[178:179], v[46:47]
	v_pk_fma_f32 v[40:41], v[12:13], v[180:181], v[40:41]
	v_pk_fma_f32 v[48:49], v[20:21], v[180:181], v[48:49]
	v_pk_fma_f32 v[42:43], v[14:15], v[182:183], v[42:43]
	v_pk_fma_f32 v[50:51], v[22:23], v[182:183], v[50:51]
	v_pk_fma_f32 v[34:35], v[200:201], v[202:203], v[34:35] op_sel:[0,1,0]
	v_pk_fma_f32 v[8:9], v[192:193], v[200:201], v[36:37] op_sel_hi:[1,0,1]
	v_pk_fma_f32 v[16:17], v[192:193], v[200:201], v[44:45] op_sel:[0,1,0]
	v_pk_fma_f32 v[10:11], v[194:195], v[200:201], v[38:39] op_sel_hi:[1,0,1]
	v_pk_fma_f32 v[18:19], v[194:195], v[200:201], v[46:47] op_sel:[0,1,0]
	v_pk_fma_f32 v[12:13], v[196:197], v[200:201], v[40:41] op_sel_hi:[1,0,1]
	v_pk_fma_f32 v[20:21], v[196:197], v[200:201], v[48:49] op_sel:[0,1,0]
	v_pk_fma_f32 v[14:15], v[198:199], v[200:201], v[42:43] op_sel_hi:[1,0,1]
	v_pk_fma_f32 v[22:23], v[198:199], v[200:201], v[50:51] op_sel:[0,1,0]
	s_and_b64 exec, s[100:101], s[98:99]
	ds_write_b64 v122, v[34:35] offset:0
	s_mov_b64 exec, s[100:101]
	ds_read_b128 v[160:163], v0 offset:3104
	ds_read_b128 v[164:167], v0 offset:3120
	ds_read_b128 v[168:171], v0 offset:3360
	ds_read_b128 v[172:175], v0 offset:3376
	ds_read_b128 v[176:179], v0 offset:3616
	ds_read_b128 v[180:183], v0 offset:3632
	ds_read_b128 v[184:187], v0 offset:3872
	ds_read_b128 v[188:191], v0 offset:3888
	ds_read_b128 v[192:195], v0 offset:4128
	ds_read_b128 v[196:199], v0 offset:4144
	ds_read_b64 v[200:201], v62 offset:3104
	ds_read_b64 v[202:203], v64 offset:3104
	s_waitcnt lgkmcnt(12)
; __device__ __forceinline__ void phase_scan(const Params& p, int wid_s, char* shm) {
;     ...
;         for (int s = 0; s < SCAN_CH; ++s) {
;           const float* rec = cb + s * SCAN_STEP_F;
;           v2f kk[4], wr8[4], w8[4], ka8[4], kd8[4];
; #pragma unroll
;           for (int c = 0; c < 4; ++c) {
;             kk[c] = *(const v2f*)(rec + 0 + c * 2);
;             wr8[c] = *(const v2f*)(rec + 64 + c * 2);
;             w8[c] = *(const v2f*)(rec + 128 + c * 2);
;             ka8[c] = *(const v2f*)(rec + 192 + c * 2);
;             kd8[c] = *(const v2f*)(rec + 256 + c * 2);
;           }
;           v2f vv = *(const v2f*)(cv + s * SCAN_STEP_F);
;           v2f krdr = *(const v2f*)(ck + s * SCAN_STEP_F);
;           v2f p0 = S0[0] * kk[0], p1 = S1[0] * kk[0], q0 = S0[0] * wr8[0], q1 = S1[0] * wr8[0];
; #pragma unroll
;           for (int c = 1; c < 4; ++c) {
;             p0 += S0[c] * kk[c]; p1 += S1[c] * kk[c];
;             q0 += S0[c] * wr8[c]; q1 += S1[c] * wr8[c];
;           }
;           float p0s = red8(p0.x + p0.y), p1s = red8(p1.x + p1.y);
;           float q0s = red8(q0.x + q0.y), q1s = red8(q1.x + q1.y);
;           float sa0 = -p0s, sa1 = -p1s;
;           v2f yy;
;           yy.x = q0s + sa0 * krdr.x + vv.x * krdr.y;
;           yy.y = q1s + sa1 * krdr.x + vv.y * krdr.y;
;           *(v2f*)(yw + s * 64) = yy;
;           v2f sa0v = v2f{sa0, sa0}, sa1v = v2f{sa1, sa1}, v0v = v2f{vv.x, vv.x}, v1v = v2f{vv.y, vv.y};
; #pragma unroll
;           for (int c = 0; c < 4; ++c) {
;             S0[c] = S0[c] * w8[c] + sa0v * ka8[c] + v0v * kd8[c];
;             S1[c] = S1[c] * w8[c] + sa1v * ka8[c] + v1v * kd8[c];
;           }
	v_pk_mul_f32 v[24:25], v[10:11], v[206:207]
	v_pk_mul_f32 v[26:27], v[18:19], v[206:207]
	v_pk_mul_f32 v[28:29], v[10:11], v[214:215]
	v_pk_mul_f32 v[30:31], v[18:19], v[214:215]
	v_pk_fma_f32 v[24:25], v[8:9], v[204:205], v[24:25]
	v_pk_fma_f32 v[26:27], v[16:17], v[204:205], v[26:27]
	v_pk_fma_f32 v[28:29], v[8:9], v[212:213], v[28:29]
	v_pk_fma_f32 v[30:31], v[16:17], v[212:213], v[30:31]
	v_pk_fma_f32 v[24:25], v[12:13], v[208:209], v[24:25]
	v_pk_fma_f32 v[26:27], v[20:21], v[208:209], v[26:27]
	v_pk_fma_f32 v[28:29], v[12:13], v[216:217], v[28:29]
	v_pk_fma_f32 v[30:31], v[20:21], v[216:217], v[30:31]
	v_pk_fma_f32 v[24:25], v[14:15], v[210:211], v[24:25]
	v_pk_fma_f32 v[26:27], v[22:23], v[210:211], v[26:27]
	v_pk_fma_f32 v[28:29], v[14:15], v[218:219], v[28:29]
	v_pk_fma_f32 v[30:31], v[22:23], v[218:219], v[30:31]
	v_add_f32_e32 v32, v24, v25
	v_add_f32_e32 v33, v26, v27
	v_add_f32_e32 v34, v28, v29
	v_add_f32_e32 v35, v30, v31
	v_add_f32_dpp v32, v32, v32 quad_perm:[1,0,3,2] row_mask:0xf bank_mask:0xf bound_ctrl:1
	v_add_f32_dpp v33, v33, v33 quad_perm:[1,0,3,2] row_mask:0xf bank_mask:0xf bound_ctrl:1
	v_add_f32_dpp v34, v34, v34 quad_perm:[1,0,3,2] row_mask:0xf bank_mask:0xf bound_ctrl:1
	v_add_f32_dpp v35, v35, v35 quad_perm:[1,0,3,2] row_mask:0xf bank_mask:0xf bound_ctrl:1
	v_add_f32_dpp v32, v32, v32 quad_perm:[2,3,0,1] row_mask:0xf bank_mask:0xf bound_ctrl:1
	v_add_f32_dpp v33, v33, v33 quad_perm:[2,3,0,1] row_mask:0xf bank_mask:0xf bound_ctrl:1
	v_add_f32_dpp v34, v34, v34 quad_perm:[2,3,0,1] row_mask:0xf bank_mask:0xf bound_ctrl:1
	v_add_f32_dpp v35, v35, v35 quad_perm:[2,3,0,1] row_mask:0xf bank_mask:0xf bound_ctrl:1
	v_add_f32_dpp v32, v32, v32 row_half_mirror row_mask:0xf bank_mask:0xf bound_ctrl:1
	v_add_f32_dpp v33, v33, v33 row_half_mirror row_mask:0xf bank_mask:0xf bound_ctrl:1
	v_add_f32_dpp v34, v34, v34 row_half_mirror row_mask:0xf bank_mask:0xf bound_ctrl:1
	v_add_f32_dpp v35, v35, v35 row_half_mirror row_mask:0xf bank_mask:0xf bound_ctrl:1
	v_pk_mul_f32 v[36:37], v[228:229], v[32:33] op_sel_hi:[1,0] neg_lo:[0,1] neg_hi:[0,1]
	v_pk_mul_f32 v[44:45], v[228:229], v[32:33] op_sel:[0,1] neg_lo:[0,1] neg_hi:[0,1]
	v_pk_mul_f32 v[38:39], v[230:231], v[32:33] op_sel_hi:[1,0] neg_lo:[0,1] neg_hi:[0,1]
	v_pk_mul_f32 v[46:47], v[230:231], v[32:33] op_sel:[0,1] neg_lo:[0,1] neg_hi:[0,1]
	v_pk_mul_f32 v[40:41], v[232:233], v[32:33] op_sel_hi:[1,0] neg_lo:[0,1] neg_hi:[0,1]
	v_pk_mul_f32 v[48:49], v[232:233], v[32:33] op_sel:[0,1] neg_lo:[0,1] neg_hi:[0,1]
	v_pk_mul_f32 v[42:43], v[234:235], v[32:33] op_sel_hi:[1,0] neg_lo:[0,1] neg_hi:[0,1]
	v_pk_mul_f32 v[50:51], v[234:235], v[32:33] op_sel:[0,1] neg_lo:[0,1] neg_hi:[0,1]
	v_pk_fma_f32 v[34:35], v[246:247], v[32:33], v[34:35] op_sel_hi:[0,1,1] neg_lo:[1,0,0] neg_hi:[1,0,0]
	v_pk_fma_f32 v[36:37], v[8:9], v[220:221], v[36:37]
	v_pk_fma_f32 v[44:45], v[16:17], v[220:221], v[44:45]
	v_pk_fma_f32 v[38:39], v[10:11], v[222:223], v[38:39]
	v_pk_fma_f32 v[46:47], v[18:19], v[222:223], v[46:47]
	v_pk_fma_f32 v[40:41], v[12:13], v[224:225], v[40:41]
	v_pk_fma_f32 v[48:49], v[20:21], v[224:225], v[48:49]
	v_pk_fma_f32 v[42:43], v[14:15], v[226:227], v[42:43]
	v_pk_fma_f32 v[50:51], v[22:23], v[226:227], v[50:51]
	v_pk_fma_f32 v[34:35], v[244:245], v[246:247], v[34:35] op_sel:[0,1,0]
	v_pk_fma_f32 v[8:9], v[236:237], v[244:245], v[36:37] op_sel_hi:[1,0,1]
	v_pk_fma_f32 v[16:17], v[236:237], v[244:245], v[44:45] op_sel:[0,1,0]
	v_pk_fma_f32 v[10:11], v[238:239], v[244:245], v[38:39] op_sel_hi:[1,0,1]
	v_pk_fma_f32 v[18:19], v[238:239], v[244:245], v[46:47] op_sel:[0,1,0]
	v_pk_fma_f32 v[12:13], v[240:241], v[244:245], v[40:41] op_sel_hi:[1,0,1]
	v_pk_fma_f32 v[20:21], v[240:241], v[244:245], v[48:49] op_sel:[0,1,0]
	v_pk_fma_f32 v[14:15], v[242:243], v[244:245], v[42:43] op_sel_hi:[1,0,1]
	v_pk_fma_f32 v[22:23], v[242:243], v[244:245], v[50:51] op_sel:[0,1,0]
	s_and_b64 exec, s[100:101], s[98:99]
	ds_write_b64 v122, v[34:35] offset:256
	s_mov_b64 exec, s[100:101]
	ds_read_b128 v[204:207], v0 offset:4656
	ds_read_b128 v[208:211], v0 offset:4672
	ds_read_b128 v[212:215], v0 offset:4912
	ds_read_b128 v[216:219], v0 offset:4928
	ds_read_b128 v[220:223], v0 offset:5168
	ds_read_b128 v[224:227], v0 offset:5184
	ds_read_b128 v[228:231], v0 offset:5424
	ds_read_b128 v[232:235], v0 offset:5440
	ds_read_b128 v[236:239], v0 offset:5680
	ds_read_b128 v[240:243], v0 offset:5696
	ds_read_b64 v[244:245], v62 offset:4656
	ds_read_b64 v[246:247], v64 offset:4656
	s_waitcnt lgkmcnt(12)
; __device__ __forceinline__ void phase_scan(const Params& p, int wid_s, char* shm) {
;     ...
;         for (int s = 0; s < SCAN_CH; ++s) {
;           const float* rec = cb + s * SCAN_STEP_F;
;           v2f kk[4], wr8[4], w8[4], ka8[4], kd8[4];
; #pragma unroll
;           for (int c = 0; c < 4; ++c) {
;             kk[c] = *(const v2f*)(rec + 0 + c * 2);
;             wr8[c] = *(const v2f*)(rec + 64 + c * 2);
;             w8[c] = *(const v2f*)(rec + 128 + c * 2);
;             ka8[c] = *(const v2f*)(rec + 192 + c * 2);
;             kd8[c] = *(const v2f*)(rec + 256 + c * 2);
;           }
;           v2f vv = *(const v2f*)(cv + s * SCAN_STEP_F);
;           v2f krdr = *(const v2f*)(ck + s * SCAN_STEP_F);
;           v2f p0 = S0[0] * kk[0], p1 = S1[0] * kk[0], q0 = S0[0] * wr8[0], q1 = S1[0] * wr8[0];
; #pragma unroll
;           for (int c = 1; c < 4; ++c) {
;             p0 += S0[c] * kk[c]; p1 += S1[c] * kk[c];
;             q0 += S0[c] * wr8[c]; q1 += S1[c] * wr8[c];
;           }
;           float p0s = red8(p0.x + p0.y), p1s = red8(p1.x + p1.y);
;           float q0s = red8(q0.x + q0.y), q1s = red8(q1.x + q1.y);
;           float sa0 = -p0s, sa1 = -p1s;
;           v2f yy;
;           yy.x = q0s + sa0 * krdr.x + vv.x * krdr.y;
;           yy.y = q1s + sa1 * krdr.x + vv.y * krdr.y;
;           *(v2f*)(yw + s * 64) = yy;
;           v2f sa0v = v2f{sa0, sa0}, sa1v = v2f{sa1, sa1}, v0v = v2f{vv.x, vv.x}, v1v = v2f{vv.y, vv.y};
; #pragma unroll
;           for (int c = 0; c < 4; ++c) {
;             S0[c] = S0[c] * w8[c] + sa0v * ka8[c] + v0v * kd8[c];
;             S1[c] = S1[c] * w8[c] + sa1v * ka8[c] + v1v * kd8[c];
;           }
	v_pk_mul_f32 v[24:25], v[10:11], v[162:163]
	v_pk_mul_f32 v[26:27], v[18:19], v[162:163]
	v_pk_mul_f32 v[28:29], v[10:11], v[170:171]
	v_pk_mul_f32 v[30:31], v[18:19], v[170:171]
	v_pk_fma_f32 v[24:25], v[8:9], v[160:161], v[24:25]
	v_pk_fma_f32 v[26:27], v[16:17], v[160:161], v[26:27]
	v_pk_fma_f32 v[28:29], v[8:9], v[168:169], v[28:29]
	v_pk_fma_f32 v[30:31], v[16:17], v[168:169], v[30:31]
	v_pk_fma_f32 v[24:25], v[12:13], v[164:165], v[24:25]
	v_pk_fma_f32 v[26:27], v[20:21], v[164:165], v[26:27]
	v_pk_fma_f32 v[28:29], v[12:13], v[172:173], v[28:29]
	v_pk_fma_f32 v[30:31], v[20:21], v[172:173], v[30:31]
	v_pk_fma_f32 v[24:25], v[14:15], v[166:167], v[24:25]
	v_pk_fma_f32 v[26:27], v[22:23], v[166:167], v[26:27]
	v_pk_fma_f32 v[28:29], v[14:15], v[174:175], v[28:29]
	v_pk_fma_f32 v[30:31], v[22:23], v[174:175], v[30:31]
	v_add_f32_e32 v32, v24, v25
	v_add_f32_e32 v33, v26, v27
	v_add_f32_e32 v34, v28, v29
	v_add_f32_e32 v35, v30, v31
	v_add_f32_dpp v32, v32, v32 quad_perm:[1,0,3,2] row_mask:0xf bank_mask:0xf bound_ctrl:1
	v_add_f32_dpp v33, v33, v33 quad_perm:[1,0,3,2] row_mask:0xf bank_mask:0xf bound_ctrl:1
	v_add_f32_dpp v34, v34, v34 quad_perm:[1,0,3,2] row_mask:0xf bank_mask:0xf bound_ctrl:1
	v_add_f32_dpp v35, v35, v35 quad_perm:[1,0,3,2] row_mask:0xf bank_mask:0xf bound_ctrl:1
	v_add_f32_dpp v32, v32, v32 quad_perm:[2,3,0,1] row_mask:0xf bank_mask:0xf bound_ctrl:1
	v_add_f32_dpp v33, v33, v33 quad_perm:[2,3,0,1] row_mask:0xf bank_mask:0xf bound_ctrl:1
	v_add_f32_dpp v34, v34, v34 quad_perm:[2,3,0,1] row_mask:0xf bank_mask:0xf bound_ctrl:1
	v_add_f32_dpp v35, v35, v35 quad_perm:[2,3,0,1] row_mask:0xf bank_mask:0xf bound_ctrl:1
	v_add_f32_dpp v32, v32, v32 row_half_mirror row_mask:0xf bank_mask:0xf bound_ctrl:1
	v_add_f32_dpp v33, v33, v33 row_half_mirror row_mask:0xf bank_mask:0xf bound_ctrl:1
	v_add_f32_dpp v34, v34, v34 row_half_mirror row_mask:0xf bank_mask:0xf bound_ctrl:1
	v_add_f32_dpp v35, v35, v35 row_half_mirror row_mask:0xf bank_mask:0xf bound_ctrl:1
	v_pk_mul_f32 v[36:37], v[184:185], v[32:33] op_sel_hi:[1,0] neg_lo:[0,1] neg_hi:[0,1]
	v_pk_mul_f32 v[44:45], v[184:185], v[32:33] op_sel:[0,1] neg_lo:[0,1] neg_hi:[0,1]
	v_pk_mul_f32 v[38:39], v[186:187], v[32:33] op_sel_hi:[1,0] neg_lo:[0,1] neg_hi:[0,1]
	v_pk_mul_f32 v[46:47], v[186:187], v[32:33] op_sel:[0,1] neg_lo:[0,1] neg_hi:[0,1]
	v_pk_mul_f32 v[40:41], v[188:189], v[32:33] op_sel_hi:[1,0] neg_lo:[0,1] neg_hi:[0,1]
	v_pk_mul_f32 v[48:49], v[188:189], v[32:33] op_sel:[0,1] neg_lo:[0,1] neg_hi:[0,1]
	v_pk_mul_f32 v[42:43], v[190:191], v[32:33] op_sel_hi:[1,0] neg_lo:[0,1] neg_hi:[0,1]
	v_pk_mul_f32 v[50:51], v[190:191], v[32:33] op_sel:[0,1] neg_lo:[0,1] neg_hi:[0,1]
	v_pk_fma_f32 v[34:35], v[202:203], v[32:33], v[34:35] op_sel_hi:[0,1,1] neg_lo:[1,0,0] neg_hi:[1,0,0]
	v_pk_fma_f32 v[36:37], v[8:9], v[176:177], v[36:37]
	v_pk_fma_f32 v[44:45], v[16:17], v[176:177], v[44:45]
	v_pk_fma_f32 v[38:39], v[10:11], v[178:179], v[38:39]
	v_pk_fma_f32 v[46:47], v[18:19], v[178:179], v[46:47]
	v_pk_fma_f32 v[40:41], v[12:13], v[180:181], v[40:41]
	v_pk_fma_f32 v[48:49], v[20:21], v[180:181], v[48:49]
	v_pk_fma_f32 v[42:43], v[14:15], v[182:183], v[42:43]
	v_pk_fma_f32 v[50:51], v[22:23], v[182:183], v[50:51]
	v_pk_fma_f32 v[34:35], v[200:201], v[202:203], v[34:35] op_sel:[0,1,0]
	v_pk_fma_f32 v[8:9], v[192:193], v[200:201], v[36:37] op_sel_hi:[1,0,1]
	v_pk_fma_f32 v[16:17], v[192:193], v[200:201], v[44:45] op_sel:[0,1,0]
	v_pk_fma_f32 v[10:11], v[194:195], v[200:201], v[38:39] op_sel_hi:[1,0,1]
	v_pk_fma_f32 v[18:19], v[194:195], v[200:201], v[46:47] op_sel:[0,1,0]
	v_pk_fma_f32 v[12:13], v[196:197], v[200:201], v[40:41] op_sel_hi:[1,0,1]
	v_pk_fma_f32 v[20:21], v[196:197], v[200:201], v[48:49] op_sel:[0,1,0]
	v_pk_fma_f32 v[14:15], v[198:199], v[200:201], v[42:43] op_sel_hi:[1,0,1]
	v_pk_fma_f32 v[22:23], v[198:199], v[200:201], v[50:51] op_sel:[0,1,0]
	s_and_b64 exec, s[100:101], s[98:99]
	ds_write_b64 v122, v[34:35] offset:512
	s_mov_b64 exec, s[100:101]
	ds_read_b128 v[160:163], v0 offset:6208
	ds_read_b128 v[164:167], v0 offset:6224
	ds_read_b128 v[168:171], v0 offset:6464
	ds_read_b128 v[172:175], v0 offset:6480
	ds_read_b128 v[176:179], v0 offset:6720
	ds_read_b128 v[180:183], v0 offset:6736
	ds_read_b128 v[184:187], v0 offset:6976
	ds_read_b128 v[188:191], v0 offset:6992
	ds_read_b128 v[192:195], v0 offset:7232
	ds_read_b128 v[196:199], v0 offset:7248
	ds_read_b64 v[200:201], v62 offset:6208
	ds_read_b64 v[202:203], v64 offset:6208
	s_waitcnt lgkmcnt(12)
; __device__ __forceinline__ void phase_scan(const Params& p, int wid_s, char* shm) {
;     ...
;         for (int s = 0; s < SCAN_CH; ++s) {
;           const float* rec = cb + s * SCAN_STEP_F;
;           v2f kk[4], wr8[4], w8[4], ka8[4], kd8[4];
; #pragma unroll
;           for (int c = 0; c < 4; ++c) {
;             kk[c] = *(const v2f*)(rec + 0 + c * 2);
;             wr8[c] = *(const v2f*)(rec + 64 + c * 2);
;             w8[c] = *(const v2f*)(rec + 128 + c * 2);
;             ka8[c] = *(const v2f*)(rec + 192 + c * 2);
;             kd8[c] = *(const v2f*)(rec + 256 + c * 2);
;           }
;           v2f vv = *(const v2f*)(cv + s * SCAN_STEP_F);
;           v2f krdr = *(const v2f*)(ck + s * SCAN_STEP_F);
;           v2f p0 = S0[0] * kk[0], p1 = S1[0] * kk[0], q0 = S0[0] * wr8[0], q1 = S1[0] * wr8[0];
; #pragma unroll
;           for (int c = 1; c < 4; ++c) {
;             p0 += S0[c] * kk[c]; p1 += S1[c] * kk[c];
;             q0 += S0[c] * wr8[c]; q1 += S1[c] * wr8[c];
;           }
;           float p0s = red8(p0.x + p0.y), p1s = red8(p1.x + p1.y);
;           float q0s = red8(q0.x + q0.y), q1s = red8(q1.x + q1.y);
;           float sa0 = -p0s, sa1 = -p1s;
;           v2f yy;
;           yy.x = q0s + sa0 * krdr.x + vv.x * krdr.y;
;           yy.y = q1s + sa1 * krdr.x + vv.y * krdr.y;
;           *(v2f*)(yw + s * 64) = yy;
;           v2f sa0v = v2f{sa0, sa0}, sa1v = v2f{sa1, sa1}, v0v = v2f{vv.x, vv.x}, v1v = v2f{vv.y, vv.y};
; #pragma unroll
;           for (int c = 0; c < 4; ++c) {
;             S0[c] = S0[c] * w8[c] + sa0v * ka8[c] + v0v * kd8[c];
;             S1[c] = S1[c] * w8[c] + sa1v * ka8[c] + v1v * kd8[c];
;           }
	v_pk_mul_f32 v[24:25], v[10:11], v[206:207]
	v_pk_mul_f32 v[26:27], v[18:19], v[206:207]
	v_pk_mul_f32 v[28:29], v[10:11], v[214:215]
	v_pk_mul_f32 v[30:31], v[18:19], v[214:215]
	v_pk_fma_f32 v[24:25], v[8:9], v[204:205], v[24:25]
	v_pk_fma_f32 v[26:27], v[16:17], v[204:205], v[26:27]
	v_pk_fma_f32 v[28:29], v[8:9], v[212:213], v[28:29]
	v_pk_fma_f32 v[30:31], v[16:17], v[212:213], v[30:31]
	v_pk_fma_f32 v[24:25], v[12:13], v[208:209], v[24:25]
	v_pk_fma_f32 v[26:27], v[20:21], v[208:209], v[26:27]
	v_pk_fma_f32 v[28:29], v[12:13], v[216:217], v[28:29]
	v_pk_fma_f32 v[30:31], v[20:21], v[216:217], v[30:31]
	v_pk_fma_f32 v[24:25], v[14:15], v[210:211], v[24:25]
	v_pk_fma_f32 v[26:27], v[22:23], v[210:211], v[26:27]
	v_pk_fma_f32 v[28:29], v[14:15], v[218:219], v[28:29]
	v_pk_fma_f32 v[30:31], v[22:23], v[218:219], v[30:31]
	v_add_f32_e32 v32, v24, v25
	v_add_f32_e32 v33, v26, v27
	v_add_f32_e32 v34, v28, v29
	v_add_f32_e32 v35, v30, v31
	v_add_f32_dpp v32, v32, v32 quad_perm:[1,0,3,2] row_mask:0xf bank_mask:0xf bound_ctrl:1
	v_add_f32_dpp v33, v33, v33 quad_perm:[1,0,3,2] row_mask:0xf bank_mask:0xf bound_ctrl:1
	v_add_f32_dpp v34, v34, v34 quad_perm:[1,0,3,2] row_mask:0xf bank_mask:0xf bound_ctrl:1
	v_add_f32_dpp v35, v35, v35 quad_perm:[1,0,3,2] row_mask:0xf bank_mask:0xf bound_ctrl:1
	v_add_f32_dpp v32, v32, v32 quad_perm:[2,3,0,1] row_mask:0xf bank_mask:0xf bound_ctrl:1
	v_add_f32_dpp v33, v33, v33 quad_perm:[2,3,0,1] row_mask:0xf bank_mask:0xf bound_ctrl:1
	v_add_f32_dpp v34, v34, v34 quad_perm:[2,3,0,1] row_mask:0xf bank_mask:0xf bound_ctrl:1
	v_add_f32_dpp v35, v35, v35 quad_perm:[2,3,0,1] row_mask:0xf bank_mask:0xf bound_ctrl:1
	v_add_f32_dpp v32, v32, v32 row_half_mirror row_mask:0xf bank_mask:0xf bound_ctrl:1
	v_add_f32_dpp v33, v33, v33 row_half_mirror row_mask:0xf bank_mask:0xf bound_ctrl:1
	v_add_f32_dpp v34, v34, v34 row_half_mirror row_mask:0xf bank_mask:0xf bound_ctrl:1
	v_add_f32_dpp v35, v35, v35 row_half_mirror row_mask:0xf bank_mask:0xf bound_ctrl:1
	v_pk_mul_f32 v[36:37], v[228:229], v[32:33] op_sel_hi:[1,0] neg_lo:[0,1] neg_hi:[0,1]
	v_pk_mul_f32 v[44:45], v[228:229], v[32:33] op_sel:[0,1] neg_lo:[0,1] neg_hi:[0,1]
	v_pk_mul_f32 v[38:39], v[230:231], v[32:33] op_sel_hi:[1,0] neg_lo:[0,1] neg_hi:[0,1]
	v_pk_mul_f32 v[46:47], v[230:231], v[32:33] op_sel:[0,1] neg_lo:[0,1] neg_hi:[0,1]
	v_pk_mul_f32 v[40:41], v[232:233], v[32:33] op_sel_hi:[1,0] neg_lo:[0,1] neg_hi:[0,1]
	v_pk_mul_f32 v[48:49], v[232:233], v[32:33] op_sel:[0,1] neg_lo:[0,1] neg_hi:[0,1]
	v_pk_mul_f32 v[42:43], v[234:235], v[32:33] op_sel_hi:[1,0] neg_lo:[0,1] neg_hi:[0,1]
	v_pk_mul_f32 v[50:51], v[234:235], v[32:33] op_sel:[0,1] neg_lo:[0,1] neg_hi:[0,1]
	v_pk_fma_f32 v[34:35], v[246:247], v[32:33], v[34:35] op_sel_hi:[0,1,1] neg_lo:[1,0,0] neg_hi:[1,0,0]
	v_pk_fma_f32 v[36:37], v[8:9], v[220:221], v[36:37]
	v_pk_fma_f32 v[44:45], v[16:17], v[220:221], v[44:45]
	v_pk_fma_f32 v[38:39], v[10:11], v[222:223], v[38:39]
	v_pk_fma_f32 v[46:47], v[18:19], v[222:223], v[46:47]
	v_pk_fma_f32 v[40:41], v[12:13], v[224:225], v[40:41]
	v_pk_fma_f32 v[48:49], v[20:21], v[224:225], v[48:49]
	v_pk_fma_f32 v[42:43], v[14:15], v[226:227], v[42:43]
	v_pk_fma_f32 v[50:51], v[22:23], v[226:227], v[50:51]
	v_pk_fma_f32 v[34:35], v[244:245], v[246:247], v[34:35] op_sel:[0,1,0]
	v_pk_fma_f32 v[8:9], v[236:237], v[244:245], v[36:37] op_sel_hi:[1,0,1]
	v_pk_fma_f32 v[16:17], v[236:237], v[244:245], v[44:45] op_sel:[0,1,0]
	v_pk_fma_f32 v[10:11], v[238:239], v[244:245], v[38:39] op_sel_hi:[1,0,1]
	v_pk_fma_f32 v[18:19], v[238:239], v[244:245], v[46:47] op_sel:[0,1,0]
	v_pk_fma_f32 v[12:13], v[240:241], v[244:245], v[40:41] op_sel_hi:[1,0,1]
	v_pk_fma_f32 v[20:21], v[240:241], v[244:245], v[48:49] op_sel:[0,1,0]
	v_pk_fma_f32 v[14:15], v[242:243], v[244:245], v[42:43] op_sel_hi:[1,0,1]
	v_pk_fma_f32 v[22:23], v[242:243], v[244:245], v[50:51] op_sel:[0,1,0]
	s_and_b64 exec, s[100:101], s[98:99]
	ds_write_b64 v122, v[34:35] offset:768
	s_mov_b64 exec, s[100:101]
	ds_read_b128 v[204:207], v0 offset:7760
	ds_read_b128 v[208:211], v0 offset:7776
	ds_read_b128 v[212:215], v0 offset:8016
	ds_read_b128 v[216:219], v0 offset:8032
	ds_read_b128 v[220:223], v0 offset:8272
	ds_read_b128 v[224:227], v0 offset:8288
	ds_read_b128 v[228:231], v0 offset:8528
	ds_read_b128 v[232:235], v0 offset:8544
	ds_read_b128 v[236:239], v0 offset:8784
	ds_read_b128 v[240:243], v0 offset:8800
	ds_read_b64 v[244:245], v62 offset:7760
	ds_read_b64 v[246:247], v64 offset:7760
	s_waitcnt lgkmcnt(12)
; __device__ __forceinline__ void phase_scan(const Params& p, int wid_s, char* shm) {
;     ...
;         for (int s = 0; s < SCAN_CH; ++s) {
;           const float* rec = cb + s * SCAN_STEP_F;
;           v2f kk[4], wr8[4], w8[4], ka8[4], kd8[4];
; #pragma unroll
;           for (int c = 0; c < 4; ++c) {
;             kk[c] = *(const v2f*)(rec + 0 + c * 2);
;             wr8[c] = *(const v2f*)(rec + 64 + c * 2);
;             w8[c] = *(const v2f*)(rec + 128 + c * 2);
;             ka8[c] = *(const v2f*)(rec + 192 + c * 2);
;             kd8[c] = *(const v2f*)(rec + 256 + c * 2);
;           }
;           v2f vv = *(const v2f*)(cv + s * SCAN_STEP_F);
;           v2f krdr = *(const v2f*)(ck + s * SCAN_STEP_F);
;           v2f p0 = S0[0] * kk[0], p1 = S1[0] * kk[0], q0 = S0[0] * wr8[0], q1 = S1[0] * wr8[0];
; #pragma unroll
;           for (int c = 1; c < 4; ++c) {
;             p0 += S0[c] * kk[c]; p1 += S1[c] * kk[c];
;             q0 += S0[c] * wr8[c]; q1 += S1[c] * wr8[c];
;           }
;           float p0s = red8(p0.x + p0.y), p1s = red8(p1.x + p1.y);
;           float q0s = red8(q0.x + q0.y), q1s = red8(q1.x + q1.y);
;           float sa0 = -p0s, sa1 = -p1s;
;           v2f yy;
;           yy.x = q0s + sa0 * krdr.x + vv.x * krdr.y;
;           yy.y = q1s + sa1 * krdr.x + vv.y * krdr.y;
;           *(v2f*)(yw + s * 64) = yy;
;           v2f sa0v = v2f{sa0, sa0}, sa1v = v2f{sa1, sa1}, v0v = v2f{vv.x, vv.x}, v1v = v2f{vv.y, vv.y};
; #pragma unroll
;           for (int c = 0; c < 4; ++c) {
;             S0[c] = S0[c] * w8[c] + sa0v * ka8[c] + v0v * kd8[c];
;             S1[c] = S1[c] * w8[c] + sa1v * ka8[c] + v1v * kd8[c];
;           }
	v_pk_mul_f32 v[24:25], v[10:11], v[162:163]
	v_pk_mul_f32 v[26:27], v[18:19], v[162:163]
	v_pk_mul_f32 v[28:29], v[10:11], v[170:171]
	v_pk_mul_f32 v[30:31], v[18:19], v[170:171]
	v_pk_fma_f32 v[24:25], v[8:9], v[160:161], v[24:25]
	v_pk_fma_f32 v[26:27], v[16:17], v[160:161], v[26:27]
	v_pk_fma_f32 v[28:29], v[8:9], v[168:169], v[28:29]
	v_pk_fma_f32 v[30:31], v[16:17], v[168:169], v[30:31]
	v_pk_fma_f32 v[24:25], v[12:13], v[164:165], v[24:25]
	v_pk_fma_f32 v[26:27], v[20:21], v[164:165], v[26:27]
	v_pk_fma_f32 v[28:29], v[12:13], v[172:173], v[28:29]
	v_pk_fma_f32 v[30:31], v[20:21], v[172:173], v[30:31]
	v_pk_fma_f32 v[24:25], v[14:15], v[166:167], v[24:25]
	v_pk_fma_f32 v[26:27], v[22:23], v[166:167], v[26:27]
	v_pk_fma_f32 v[28:29], v[14:15], v[174:175], v[28:29]
	v_pk_fma_f32 v[30:31], v[22:23], v[174:175], v[30:31]
	v_add_f32_e32 v32, v24, v25
	v_add_f32_e32 v33, v26, v27
	v_add_f32_e32 v34, v28, v29
	v_add_f32_e32 v35, v30, v31
	v_add_f32_dpp v32, v32, v32 quad_perm:[1,0,3,2] row_mask:0xf bank_mask:0xf bound_ctrl:1
	v_add_f32_dpp v33, v33, v33 quad_perm:[1,0,3,2] row_mask:0xf bank_mask:0xf bound_ctrl:1
	v_add_f32_dpp v34, v34, v34 quad_perm:[1,0,3,2] row_mask:0xf bank_mask:0xf bound_ctrl:1
	v_add_f32_dpp v35, v35, v35 quad_perm:[1,0,3,2] row_mask:0xf bank_mask:0xf bound_ctrl:1
	v_add_f32_dpp v32, v32, v32 quad_perm:[2,3,0,1] row_mask:0xf bank_mask:0xf bound_ctrl:1
	v_add_f32_dpp v33, v33, v33 quad_perm:[2,3,0,1] row_mask:0xf bank_mask:0xf bound_ctrl:1
	v_add_f32_dpp v34, v34, v34 quad_perm:[2,3,0,1] row_mask:0xf bank_mask:0xf bound_ctrl:1
	v_add_f32_dpp v35, v35, v35 quad_perm:[2,3,0,1] row_mask:0xf bank_mask:0xf bound_ctrl:1
	v_add_f32_dpp v32, v32, v32 row_half_mirror row_mask:0xf bank_mask:0xf bound_ctrl:1
	v_add_f32_dpp v33, v33, v33 row_half_mirror row_mask:0xf bank_mask:0xf bound_ctrl:1
	v_add_f32_dpp v34, v34, v34 row_half_mirror row_mask:0xf bank_mask:0xf bound_ctrl:1
	v_add_f32_dpp v35, v35, v35 row_half_mirror row_mask:0xf bank_mask:0xf bound_ctrl:1
	v_pk_mul_f32 v[36:37], v[184:185], v[32:33] op_sel_hi:[1,0] neg_lo:[0,1] neg_hi:[0,1]
	v_pk_mul_f32 v[44:45], v[184:185], v[32:33] op_sel:[0,1] neg_lo:[0,1] neg_hi:[0,1]
	v_pk_mul_f32 v[38:39], v[186:187], v[32:33] op_sel_hi:[1,0] neg_lo:[0,1] neg_hi:[0,1]
	v_pk_mul_f32 v[46:47], v[186:187], v[32:33] op_sel:[0,1] neg_lo:[0,1] neg_hi:[0,1]
	v_pk_mul_f32 v[40:41], v[188:189], v[32:33] op_sel_hi:[1,0] neg_lo:[0,1] neg_hi:[0,1]
	v_pk_mul_f32 v[48:49], v[188:189], v[32:33] op_sel:[0,1] neg_lo:[0,1] neg_hi:[0,1]
	v_pk_mul_f32 v[42:43], v[190:191], v[32:33] op_sel_hi:[1,0] neg_lo:[0,1] neg_hi:[0,1]
	v_pk_mul_f32 v[50:51], v[190:191], v[32:33] op_sel:[0,1] neg_lo:[0,1] neg_hi:[0,1]
	v_pk_fma_f32 v[34:35], v[202:203], v[32:33], v[34:35] op_sel_hi:[0,1,1] neg_lo:[1,0,0] neg_hi:[1,0,0]
	v_pk_fma_f32 v[36:37], v[8:9], v[176:177], v[36:37]
	v_pk_fma_f32 v[44:45], v[16:17], v[176:177], v[44:45]
	v_pk_fma_f32 v[38:39], v[10:11], v[178:179], v[38:39]
	v_pk_fma_f32 v[46:47], v[18:19], v[178:179], v[46:47]
	v_pk_fma_f32 v[40:41], v[12:13], v[180:181], v[40:41]
	v_pk_fma_f32 v[48:49], v[20:21], v[180:181], v[48:49]
	v_pk_fma_f32 v[42:43], v[14:15], v[182:183], v[42:43]
	v_pk_fma_f32 v[50:51], v[22:23], v[182:183], v[50:51]
	v_pk_fma_f32 v[34:35], v[200:201], v[202:203], v[34:35] op_sel:[0,1,0]
	v_pk_fma_f32 v[8:9], v[192:193], v[200:201], v[36:37] op_sel_hi:[1,0,1]
	v_pk_fma_f32 v[16:17], v[192:193], v[200:201], v[44:45] op_sel:[0,1,0]
	v_pk_fma_f32 v[10:11], v[194:195], v[200:201], v[38:39] op_sel_hi:[1,0,1]
	v_pk_fma_f32 v[18:19], v[194:195], v[200:201], v[46:47] op_sel:[0,1,0]
	v_pk_fma_f32 v[12:13], v[196:197], v[200:201], v[40:41] op_sel_hi:[1,0,1]
	v_pk_fma_f32 v[20:21], v[196:197], v[200:201], v[48:49] op_sel:[0,1,0]
	v_pk_fma_f32 v[14:15], v[198:199], v[200:201], v[42:43] op_sel_hi:[1,0,1]
	v_pk_fma_f32 v[22:23], v[198:199], v[200:201], v[50:51] op_sel:[0,1,0]
	s_and_b64 exec, s[100:101], s[98:99]
	ds_write_b64 v122, v[34:35] offset:1024
	s_mov_b64 exec, s[100:101]
	ds_read_b128 v[160:163], v0 offset:9312
	ds_read_b128 v[164:167], v0 offset:9328
	ds_read_b128 v[168:171], v0 offset:9568
	ds_read_b128 v[172:175], v0 offset:9584
	ds_read_b128 v[176:179], v0 offset:9824
	ds_read_b128 v[180:183], v0 offset:9840
	ds_read_b128 v[184:187], v0 offset:10080
	ds_read_b128 v[188:191], v0 offset:10096
	ds_read_b128 v[192:195], v0 offset:10336
	ds_read_b128 v[196:199], v0 offset:10352
	ds_read_b64 v[200:201], v62 offset:9312
	ds_read_b64 v[202:203], v64 offset:9312
	s_waitcnt lgkmcnt(12)
; __device__ __forceinline__ void phase_scan(const Params& p, int wid_s, char* shm) {
;     ...
;         for (int s = 0; s < SCAN_CH; ++s) {
;           const float* rec = cb + s * SCAN_STEP_F;
;           v2f kk[4], wr8[4], w8[4], ka8[4], kd8[4];
; #pragma unroll
;           for (int c = 0; c < 4; ++c) {
;             kk[c] = *(const v2f*)(rec + 0 + c * 2);
;             wr8[c] = *(const v2f*)(rec + 64 + c * 2);
;             w8[c] = *(const v2f*)(rec + 128 + c * 2);
;             ka8[c] = *(const v2f*)(rec + 192 + c * 2);
;             kd8[c] = *(const v2f*)(rec + 256 + c * 2);
;           }
;           v2f vv = *(const v2f*)(cv + s * SCAN_STEP_F);
;           v2f krdr = *(const v2f*)(ck + s * SCAN_STEP_F);
;           v2f p0 = S0[0] * kk[0], p1 = S1[0] * kk[0], q0 = S0[0] * wr8[0], q1 = S1[0] * wr8[0];
; #pragma unroll
;           for (int c = 1; c < 4; ++c) {
;             p0 += S0[c] * kk[c]; p1 += S1[c] * kk[c];
;             q0 += S0[c] * wr8[c]; q1 += S1[c] * wr8[c];
;           }
;           float p0s = red8(p0.x + p0.y), p1s = red8(p1.x + p1.y);
;           float q0s = red8(q0.x + q0.y), q1s = red8(q1.x + q1.y);
;           float sa0 = -p0s, sa1 = -p1s;
;           v2f yy;
;           yy.x = q0s + sa0 * krdr.x + vv.x * krdr.y;
;           yy.y = q1s + sa1 * krdr.x + vv.y * krdr.y;
;           *(v2f*)(yw + s * 64) = yy;
;           v2f sa0v = v2f{sa0, sa0}, sa1v = v2f{sa1, sa1}, v0v = v2f{vv.x, vv.x}, v1v = v2f{vv.y, vv.y};
; #pragma unroll
;           for (int c = 0; c < 4; ++c) {
;             S0[c] = S0[c] * w8[c] + sa0v * ka8[c] + v0v * kd8[c];
;             S1[c] = S1[c] * w8[c] + sa1v * ka8[c] + v1v * kd8[c];
;           }
	v_pk_mul_f32 v[24:25], v[10:11], v[206:207]
	v_pk_mul_f32 v[26:27], v[18:19], v[206:207]
	v_pk_mul_f32 v[28:29], v[10:11], v[214:215]
	v_pk_mul_f32 v[30:31], v[18:19], v[214:215]
	v_pk_fma_f32 v[24:25], v[8:9], v[204:205], v[24:25]
	v_pk_fma_f32 v[26:27], v[16:17], v[204:205], v[26:27]
	v_pk_fma_f32 v[28:29], v[8:9], v[212:213], v[28:29]
	v_pk_fma_f32 v[30:31], v[16:17], v[212:213], v[30:31]
	v_pk_fma_f32 v[24:25], v[12:13], v[208:209], v[24:25]
	v_pk_fma_f32 v[26:27], v[20:21], v[208:209], v[26:27]
	v_pk_fma_f32 v[28:29], v[12:13], v[216:217], v[28:29]
	v_pk_fma_f32 v[30:31], v[20:21], v[216:217], v[30:31]
	v_pk_fma_f32 v[24:25], v[14:15], v[210:211], v[24:25]
	v_pk_fma_f32 v[26:27], v[22:23], v[210:211], v[26:27]
	v_pk_fma_f32 v[28:29], v[14:15], v[218:219], v[28:29]
	v_pk_fma_f32 v[30:31], v[22:23], v[218:219], v[30:31]
	v_add_f32_e32 v32, v24, v25
	v_add_f32_e32 v33, v26, v27
	v_add_f32_e32 v34, v28, v29
	v_add_f32_e32 v35, v30, v31
	v_add_f32_dpp v32, v32, v32 quad_perm:[1,0,3,2] row_mask:0xf bank_mask:0xf bound_ctrl:1
	v_add_f32_dpp v33, v33, v33 quad_perm:[1,0,3,2] row_mask:0xf bank_mask:0xf bound_ctrl:1
	v_add_f32_dpp v34, v34, v34 quad_perm:[1,0,3,2] row_mask:0xf bank_mask:0xf bound_ctrl:1
	v_add_f32_dpp v35, v35, v35 quad_perm:[1,0,3,2] row_mask:0xf bank_mask:0xf bound_ctrl:1
	v_add_f32_dpp v32, v32, v32 quad_perm:[2,3,0,1] row_mask:0xf bank_mask:0xf bound_ctrl:1
	v_add_f32_dpp v33, v33, v33 quad_perm:[2,3,0,1] row_mask:0xf bank_mask:0xf bound_ctrl:1
	v_add_f32_dpp v34, v34, v34 quad_perm:[2,3,0,1] row_mask:0xf bank_mask:0xf bound_ctrl:1
	v_add_f32_dpp v35, v35, v35 quad_perm:[2,3,0,1] row_mask:0xf bank_mask:0xf bound_ctrl:1
	v_add_f32_dpp v32, v32, v32 row_half_mirror row_mask:0xf bank_mask:0xf bound_ctrl:1
	v_add_f32_dpp v33, v33, v33 row_half_mirror row_mask:0xf bank_mask:0xf bound_ctrl:1
	v_add_f32_dpp v34, v34, v34 row_half_mirror row_mask:0xf bank_mask:0xf bound_ctrl:1
	v_add_f32_dpp v35, v35, v35 row_half_mirror row_mask:0xf bank_mask:0xf bound_ctrl:1
	v_pk_mul_f32 v[36:37], v[228:229], v[32:33] op_sel_hi:[1,0] neg_lo:[0,1] neg_hi:[0,1]
	v_pk_mul_f32 v[44:45], v[228:229], v[32:33] op_sel:[0,1] neg_lo:[0,1] neg_hi:[0,1]
	v_pk_mul_f32 v[38:39], v[230:231], v[32:33] op_sel_hi:[1,0] neg_lo:[0,1] neg_hi:[0,1]
	v_pk_mul_f32 v[46:47], v[230:231], v[32:33] op_sel:[0,1] neg_lo:[0,1] neg_hi:[0,1]
	v_pk_mul_f32 v[40:41], v[232:233], v[32:33] op_sel_hi:[1,0] neg_lo:[0,1] neg_hi:[0,1]
	v_pk_mul_f32 v[48:49], v[232:233], v[32:33] op_sel:[0,1] neg_lo:[0,1] neg_hi:[0,1]
	v_pk_mul_f32 v[42:43], v[234:235], v[32:33] op_sel_hi:[1,0] neg_lo:[0,1] neg_hi:[0,1]
	v_pk_mul_f32 v[50:51], v[234:235], v[32:33] op_sel:[0,1] neg_lo:[0,1] neg_hi:[0,1]
	v_pk_fma_f32 v[34:35], v[246:247], v[32:33], v[34:35] op_sel_hi:[0,1,1] neg_lo:[1,0,0] neg_hi:[1,0,0]
	v_pk_fma_f32 v[36:37], v[8:9], v[220:221], v[36:37]
	v_pk_fma_f32 v[44:45], v[16:17], v[220:221], v[44:45]
	v_pk_fma_f32 v[38:39], v[10:11], v[222:223], v[38:39]
	v_pk_fma_f32 v[46:47], v[18:19], v[222:223], v[46:47]
	v_pk_fma_f32 v[40:41], v[12:13], v[224:225], v[40:41]
	v_pk_fma_f32 v[48:49], v[20:21], v[224:225], v[48:49]
	v_pk_fma_f32 v[42:43], v[14:15], v[226:227], v[42:43]
	v_pk_fma_f32 v[50:51], v[22:23], v[226:227], v[50:51]
	v_pk_fma_f32 v[34:35], v[244:245], v[246:247], v[34:35] op_sel:[0,1,0]
	v_pk_fma_f32 v[8:9], v[236:237], v[244:245], v[36:37] op_sel_hi:[1,0,1]
	v_pk_fma_f32 v[16:17], v[236:237], v[244:245], v[44:45] op_sel:[0,1,0]
	v_pk_fma_f32 v[10:11], v[238:239], v[244:245], v[38:39] op_sel_hi:[1,0,1]
	v_pk_fma_f32 v[18:19], v[238:239], v[244:245], v[46:47] op_sel:[0,1,0]
	v_pk_fma_f32 v[12:13], v[240:241], v[244:245], v[40:41] op_sel_hi:[1,0,1]
	v_pk_fma_f32 v[20:21], v[240:241], v[244:245], v[48:49] op_sel:[0,1,0]
	v_pk_fma_f32 v[14:15], v[242:243], v[244:245], v[42:43] op_sel_hi:[1,0,1]
	v_pk_fma_f32 v[22:23], v[242:243], v[244:245], v[50:51] op_sel:[0,1,0]
	s_and_b64 exec, s[100:101], s[98:99]
	ds_write_b64 v122, v[34:35] offset:1280
	s_mov_b64 exec, s[100:101]
	ds_read_b128 v[204:207], v0 offset:10864
	ds_read_b128 v[208:211], v0 offset:10880
	ds_read_b128 v[212:215], v0 offset:11120
	ds_read_b128 v[216:219], v0 offset:11136
	ds_read_b128 v[220:223], v0 offset:11376
	ds_read_b128 v[224:227], v0 offset:11392
	ds_read_b128 v[228:231], v0 offset:11632
	ds_read_b128 v[232:235], v0 offset:11648
	ds_read_b128 v[236:239], v0 offset:11888
	ds_read_b128 v[240:243], v0 offset:11904
	ds_read_b64 v[244:245], v62 offset:10864
	ds_read_b64 v[246:247], v64 offset:10864
	s_waitcnt lgkmcnt(12)
; __device__ __forceinline__ void phase_scan(const Params& p, int wid_s, char* shm) {
;     ...
;         for (int s = 0; s < SCAN_CH; ++s) {
;           const float* rec = cb + s * SCAN_STEP_F;
;           v2f kk[4], wr8[4], w8[4], ka8[4], kd8[4];
; #pragma unroll
;           for (int c = 0; c < 4; ++c) {
;             kk[c] = *(const v2f*)(rec + 0 + c * 2);
;             wr8[c] = *(const v2f*)(rec + 64 + c * 2);
;             w8[c] = *(const v2f*)(rec + 128 + c * 2);
;             ka8[c] = *(const v2f*)(rec + 192 + c * 2);
;             kd8[c] = *(const v2f*)(rec + 256 + c * 2);
;           }
;           v2f vv = *(const v2f*)(cv + s * SCAN_STEP_F);
;           v2f krdr = *(const v2f*)(ck + s * SCAN_STEP_F);
;           v2f p0 = S0[0] * kk[0], p1 = S1[0] * kk[0], q0 = S0[0] * wr8[0], q1 = S1[0] * wr8[0];
; #pragma unroll
;           for (int c = 1; c < 4; ++c) {
;             p0 += S0[c] * kk[c]; p1 += S1[c] * kk[c];
;             q0 += S0[c] * wr8[c]; q1 += S1[c] * wr8[c];
;           }
;           float p0s = red8(p0.x + p0.y), p1s = red8(p1.x + p1.y);
;           float q0s = red8(q0.x + q0.y), q1s = red8(q1.x + q1.y);
;           float sa0 = -p0s, sa1 = -p1s;
;           v2f yy;
;           yy.x = q0s + sa0 * krdr.x + vv.x * krdr.y;
;           yy.y = q1s + sa1 * krdr.x + vv.y * krdr.y;
;           *(v2f*)(yw + s * 64) = yy;
;           v2f sa0v = v2f{sa0, sa0}, sa1v = v2f{sa1, sa1}, v0v = v2f{vv.x, vv.x}, v1v = v2f{vv.y, vv.y};
; #pragma unroll
;           for (int c = 0; c < 4; ++c) {
;             S0[c] = S0[c] * w8[c] + sa0v * ka8[c] + v0v * kd8[c];
;             S1[c] = S1[c] * w8[c] + sa1v * ka8[c] + v1v * kd8[c];
;           }
	v_pk_mul_f32 v[24:25], v[10:11], v[162:163]
	v_pk_mul_f32 v[26:27], v[18:19], v[162:163]
	v_pk_mul_f32 v[28:29], v[10:11], v[170:171]
	v_pk_mul_f32 v[30:31], v[18:19], v[170:171]
	v_pk_fma_f32 v[24:25], v[8:9], v[160:161], v[24:25]
	v_pk_fma_f32 v[26:27], v[16:17], v[160:161], v[26:27]
	v_pk_fma_f32 v[28:29], v[8:9], v[168:169], v[28:29]
	v_pk_fma_f32 v[30:31], v[16:17], v[168:169], v[30:31]
	v_pk_fma_f32 v[24:25], v[12:13], v[164:165], v[24:25]
	v_pk_fma_f32 v[26:27], v[20:21], v[164:165], v[26:27]
	v_pk_fma_f32 v[28:29], v[12:13], v[172:173], v[28:29]
	v_pk_fma_f32 v[30:31], v[20:21], v[172:173], v[30:31]
	v_pk_fma_f32 v[24:25], v[14:15], v[166:167], v[24:25]
	v_pk_fma_f32 v[26:27], v[22:23], v[166:167], v[26:27]
	v_pk_fma_f32 v[28:29], v[14:15], v[174:175], v[28:29]
	v_pk_fma_f32 v[30:31], v[22:23], v[174:175], v[30:31]
	v_add_f32_e32 v32, v24, v25
	v_add_f32_e32 v33, v26, v27
	v_add_f32_e32 v34, v28, v29
	v_add_f32_e32 v35, v30, v31
	v_add_f32_dpp v32, v32, v32 quad_perm:[1,0,3,2] row_mask:0xf bank_mask:0xf bound_ctrl:1
	v_add_f32_dpp v33, v33, v33 quad_perm:[1,0,3,2] row_mask:0xf bank_mask:0xf bound_ctrl:1
	v_add_f32_dpp v34, v34, v34 quad_perm:[1,0,3,2] row_mask:0xf bank_mask:0xf bound_ctrl:1
	v_add_f32_dpp v35, v35, v35 quad_perm:[1,0,3,2] row_mask:0xf bank_mask:0xf bound_ctrl:1
	v_add_f32_dpp v32, v32, v32 quad_perm:[2,3,0,1] row_mask:0xf bank_mask:0xf bound_ctrl:1
	v_add_f32_dpp v33, v33, v33 quad_perm:[2,3,0,1] row_mask:0xf bank_mask:0xf bound_ctrl:1
	v_add_f32_dpp v34, v34, v34 quad_perm:[2,3,0,1] row_mask:0xf bank_mask:0xf bound_ctrl:1
	v_add_f32_dpp v35, v35, v35 quad_perm:[2,3,0,1] row_mask:0xf bank_mask:0xf bound_ctrl:1
	v_add_f32_dpp v32, v32, v32 row_half_mirror row_mask:0xf bank_mask:0xf bound_ctrl:1
	v_add_f32_dpp v33, v33, v33 row_half_mirror row_mask:0xf bank_mask:0xf bound_ctrl:1
	v_add_f32_dpp v34, v34, v34 row_half_mirror row_mask:0xf bank_mask:0xf bound_ctrl:1
	v_add_f32_dpp v35, v35, v35 row_half_mirror row_mask:0xf bank_mask:0xf bound_ctrl:1
	v_pk_mul_f32 v[36:37], v[184:185], v[32:33] op_sel_hi:[1,0] neg_lo:[0,1] neg_hi:[0,1]
	v_pk_mul_f32 v[44:45], v[184:185], v[32:33] op_sel:[0,1] neg_lo:[0,1] neg_hi:[0,1]
	v_pk_mul_f32 v[38:39], v[186:187], v[32:33] op_sel_hi:[1,0] neg_lo:[0,1] neg_hi:[0,1]
	v_pk_mul_f32 v[46:47], v[186:187], v[32:33] op_sel:[0,1] neg_lo:[0,1] neg_hi:[0,1]
	v_pk_mul_f32 v[40:41], v[188:189], v[32:33] op_sel_hi:[1,0] neg_lo:[0,1] neg_hi:[0,1]
	v_pk_mul_f32 v[48:49], v[188:189], v[32:33] op_sel:[0,1] neg_lo:[0,1] neg_hi:[0,1]
	v_pk_mul_f32 v[42:43], v[190:191], v[32:33] op_sel_hi:[1,0] neg_lo:[0,1] neg_hi:[0,1]
	v_pk_mul_f32 v[50:51], v[190:191], v[32:33] op_sel:[0,1] neg_lo:[0,1] neg_hi:[0,1]
	v_pk_fma_f32 v[34:35], v[202:203], v[32:33], v[34:35] op_sel_hi:[0,1,1] neg_lo:[1,0,0] neg_hi:[1,0,0]
	v_pk_fma_f32 v[36:37], v[8:9], v[176:177], v[36:37]
	v_pk_fma_f32 v[44:45], v[16:17], v[176:177], v[44:45]
	v_pk_fma_f32 v[38:39], v[10:11], v[178:179], v[38:39]
	v_pk_fma_f32 v[46:47], v[18:19], v[178:179], v[46:47]
	v_pk_fma_f32 v[40:41], v[12:13], v[180:181], v[40:41]
	v_pk_fma_f32 v[48:49], v[20:21], v[180:181], v[48:49]
	v_pk_fma_f32 v[42:43], v[14:15], v[182:183], v[42:43]
	v_pk_fma_f32 v[50:51], v[22:23], v[182:183], v[50:51]
	v_pk_fma_f32 v[34:35], v[200:201], v[202:203], v[34:35] op_sel:[0,1,0]
	v_pk_fma_f32 v[8:9], v[192:193], v[200:201], v[36:37] op_sel_hi:[1,0,1]
	v_pk_fma_f32 v[16:17], v[192:193], v[200:201], v[44:45] op_sel:[0,1,0]
	v_pk_fma_f32 v[10:11], v[194:195], v[200:201], v[38:39] op_sel_hi:[1,0,1]
	v_pk_fma_f32 v[18:19], v[194:195], v[200:201], v[46:47] op_sel:[0,1,0]
	v_pk_fma_f32 v[12:13], v[196:197], v[200:201], v[40:41] op_sel_hi:[1,0,1]
	v_pk_fma_f32 v[20:21], v[196:197], v[200:201], v[48:49] op_sel:[0,1,0]
	v_pk_fma_f32 v[14:15], v[198:199], v[200:201], v[42:43] op_sel_hi:[1,0,1]
	v_pk_fma_f32 v[22:23], v[198:199], v[200:201], v[50:51] op_sel:[0,1,0]
	s_and_b64 exec, s[100:101], s[98:99]
	ds_write_b64 v122, v[34:35] offset:1536
	s_mov_b64 exec, s[100:101]
	ds_read_b128 v[160:163], v0 offset:12416
	ds_read_b128 v[164:167], v0 offset:12432
	ds_read_b128 v[168:171], v0 offset:12672
	ds_read_b128 v[172:175], v0 offset:12688
	ds_read_b128 v[176:179], v0 offset:12928
	ds_read_b128 v[180:183], v0 offset:12944
	ds_read_b128 v[184:187], v0 offset:13184
	ds_read_b128 v[188:191], v0 offset:13200
	ds_read_b128 v[192:195], v0 offset:13440
	ds_read_b128 v[196:199], v0 offset:13456
	ds_read_b64 v[200:201], v62 offset:12416
	ds_read_b64 v[202:203], v64 offset:12416
	v_add_u32_e32 v0, 0x3080, v0
	v_add_u32_e32 v62, 0x3080, v62
	v_add_u32_e32 v64, 0x3080, v64
	v_add_u32_e32 v79, 0x800, v79
	s_add_i32 s42, s42, -8
	s_waitcnt lgkmcnt(12)
; __device__ __forceinline__ void phase_scan(const Params& p, int wid_s, char* shm) {
;     ...
;         for (int s = 0; s < SCAN_CH; ++s) {
;           const float* rec = cb + s * SCAN_STEP_F;
;           v2f kk[4], wr8[4], w8[4], ka8[4], kd8[4];
; #pragma unroll
;           for (int c = 0; c < 4; ++c) {
;             kk[c] = *(const v2f*)(rec + 0 + c * 2);
;             wr8[c] = *(const v2f*)(rec + 64 + c * 2);
;             w8[c] = *(const v2f*)(rec + 128 + c * 2);
;             ka8[c] = *(const v2f*)(rec + 192 + c * 2);
;             kd8[c] = *(const v2f*)(rec + 256 + c * 2);
;           }
;           v2f vv = *(const v2f*)(cv + s * SCAN_STEP_F);
;           v2f krdr = *(const v2f*)(ck + s * SCAN_STEP_F);
;           v2f p0 = S0[0] * kk[0], p1 = S1[0] * kk[0], q0 = S0[0] * wr8[0], q1 = S1[0] * wr8[0];
; #pragma unroll
;           for (int c = 1; c < 4; ++c) {
;             p0 += S0[c] * kk[c]; p1 += S1[c] * kk[c];
;             q0 += S0[c] * wr8[c]; q1 += S1[c] * wr8[c];
;           }
;           float p0s = red8(p0.x + p0.y), p1s = red8(p1.x + p1.y);
;           float q0s = red8(q0.x + q0.y), q1s = red8(q1.x + q1.y);
;           float sa0 = -p0s, sa1 = -p1s;
;           v2f yy;
;           yy.x = q0s + sa0 * krdr.x + vv.x * krdr.y;
;           yy.y = q1s + sa1 * krdr.x + vv.y * krdr.y;
;           *(v2f*)(yw + s * 64) = yy;
;           v2f sa0v = v2f{sa0, sa0}, sa1v = v2f{sa1, sa1}, v0v = v2f{vv.x, vv.x}, v1v = v2f{vv.y, vv.y};
; #pragma unroll
;           for (int c = 0; c < 4; ++c) {
;             S0[c] = S0[c] * w8[c] + sa0v * ka8[c] + v0v * kd8[c];
;             S1[c] = S1[c] * w8[c] + sa1v * ka8[c] + v1v * kd8[c];
;           }
	v_pk_mul_f32 v[24:25], v[10:11], v[206:207]
	v_pk_mul_f32 v[26:27], v[18:19], v[206:207]
	v_pk_mul_f32 v[28:29], v[10:11], v[214:215]
	v_pk_mul_f32 v[30:31], v[18:19], v[214:215]
	v_pk_fma_f32 v[24:25], v[8:9], v[204:205], v[24:25]
	v_pk_fma_f32 v[26:27], v[16:17], v[204:205], v[26:27]
	v_pk_fma_f32 v[28:29], v[8:9], v[212:213], v[28:29]
	v_pk_fma_f32 v[30:31], v[16:17], v[212:213], v[30:31]
	v_pk_fma_f32 v[24:25], v[12:13], v[208:209], v[24:25]
	v_pk_fma_f32 v[26:27], v[20:21], v[208:209], v[26:27]
	v_pk_fma_f32 v[28:29], v[12:13], v[216:217], v[28:29]
	v_pk_fma_f32 v[30:31], v[20:21], v[216:217], v[30:31]
	v_pk_fma_f32 v[24:25], v[14:15], v[210:211], v[24:25]
	v_pk_fma_f32 v[26:27], v[22:23], v[210:211], v[26:27]
	v_pk_fma_f32 v[28:29], v[14:15], v[218:219], v[28:29]
	v_pk_fma_f32 v[30:31], v[22:23], v[218:219], v[30:31]
	v_add_f32_e32 v32, v24, v25
	v_add_f32_e32 v33, v26, v27
	v_add_f32_e32 v34, v28, v29
	v_add_f32_e32 v35, v30, v31
	v_add_f32_dpp v32, v32, v32 quad_perm:[1,0,3,2] row_mask:0xf bank_mask:0xf bound_ctrl:1
	v_add_f32_dpp v33, v33, v33 quad_perm:[1,0,3,2] row_mask:0xf bank_mask:0xf bound_ctrl:1
	v_add_f32_dpp v34, v34, v34 quad_perm:[1,0,3,2] row_mask:0xf bank_mask:0xf bound_ctrl:1
	v_add_f32_dpp v35, v35, v35 quad_perm:[1,0,3,2] row_mask:0xf bank_mask:0xf bound_ctrl:1
	v_add_f32_dpp v32, v32, v32 quad_perm:[2,3,0,1] row_mask:0xf bank_mask:0xf bound_ctrl:1
	v_add_f32_dpp v33, v33, v33 quad_perm:[2,3,0,1] row_mask:0xf bank_mask:0xf bound_ctrl:1
	v_add_f32_dpp v34, v34, v34 quad_perm:[2,3,0,1] row_mask:0xf bank_mask:0xf bound_ctrl:1
	v_add_f32_dpp v35, v35, v35 quad_perm:[2,3,0,1] row_mask:0xf bank_mask:0xf bound_ctrl:1
	v_add_f32_dpp v32, v32, v32 row_half_mirror row_mask:0xf bank_mask:0xf bound_ctrl:1
	v_add_f32_dpp v33, v33, v33 row_half_mirror row_mask:0xf bank_mask:0xf bound_ctrl:1
	v_add_f32_dpp v34, v34, v34 row_half_mirror row_mask:0xf bank_mask:0xf bound_ctrl:1
	v_add_f32_dpp v35, v35, v35 row_half_mirror row_mask:0xf bank_mask:0xf bound_ctrl:1
	v_pk_mul_f32 v[36:37], v[228:229], v[32:33] op_sel_hi:[1,0] neg_lo:[0,1] neg_hi:[0,1]
	v_pk_mul_f32 v[44:45], v[228:229], v[32:33] op_sel:[0,1] neg_lo:[0,1] neg_hi:[0,1]
	v_pk_mul_f32 v[38:39], v[230:231], v[32:33] op_sel_hi:[1,0] neg_lo:[0,1] neg_hi:[0,1]
	v_pk_mul_f32 v[46:47], v[230:231], v[32:33] op_sel:[0,1] neg_lo:[0,1] neg_hi:[0,1]
	v_pk_mul_f32 v[40:41], v[232:233], v[32:33] op_sel_hi:[1,0] neg_lo:[0,1] neg_hi:[0,1]
	v_pk_mul_f32 v[48:49], v[232:233], v[32:33] op_sel:[0,1] neg_lo:[0,1] neg_hi:[0,1]
	v_pk_mul_f32 v[42:43], v[234:235], v[32:33] op_sel_hi:[1,0] neg_lo:[0,1] neg_hi:[0,1]
	v_pk_mul_f32 v[50:51], v[234:235], v[32:33] op_sel:[0,1] neg_lo:[0,1] neg_hi:[0,1]
	v_pk_fma_f32 v[34:35], v[246:247], v[32:33], v[34:35] op_sel_hi:[0,1,1] neg_lo:[1,0,0] neg_hi:[1,0,0]
	v_pk_fma_f32 v[36:37], v[8:9], v[220:221], v[36:37]
	v_pk_fma_f32 v[44:45], v[16:17], v[220:221], v[44:45]
	v_pk_fma_f32 v[38:39], v[10:11], v[222:223], v[38:39]
	v_pk_fma_f32 v[46:47], v[18:19], v[222:223], v[46:47]
	v_pk_fma_f32 v[40:41], v[12:13], v[224:225], v[40:41]
	v_pk_fma_f32 v[48:49], v[20:21], v[224:225], v[48:49]
	v_pk_fma_f32 v[42:43], v[14:15], v[226:227], v[42:43]
	v_pk_fma_f32 v[50:51], v[22:23], v[226:227], v[50:51]
	v_pk_fma_f32 v[34:35], v[244:245], v[246:247], v[34:35] op_sel:[0,1,0]
	v_pk_fma_f32 v[8:9], v[236:237], v[244:245], v[36:37] op_sel_hi:[1,0,1]
	v_pk_fma_f32 v[16:17], v[236:237], v[244:245], v[44:45] op_sel:[0,1,0]
	v_pk_fma_f32 v[10:11], v[238:239], v[244:245], v[38:39] op_sel_hi:[1,0,1]
	v_pk_fma_f32 v[18:19], v[238:239], v[244:245], v[46:47] op_sel:[0,1,0]
	v_pk_fma_f32 v[12:13], v[240:241], v[244:245], v[40:41] op_sel_hi:[1,0,1]
	v_pk_fma_f32 v[20:21], v[240:241], v[244:245], v[48:49] op_sel:[0,1,0]
	v_pk_fma_f32 v[14:15], v[242:243], v[244:245], v[42:43] op_sel_hi:[1,0,1]
	v_pk_fma_f32 v[22:23], v[242:243], v[244:245], v[50:51] op_sel:[0,1,0]
	s_and_b64 exec, s[100:101], s[98:99]
	ds_write_b64 v122, v[34:35] offset:1792
	s_mov_b64 exec, s[100:101]
	s_cmp_lg_u32 s42, 0
	s_cbranch_scc1 .LBB0_866
